# ret_out tile: causal 16-token blocks re-dealt across the four waves as {w,7-w} (equal inner-loop trip counts), on top of gMLP LN-stat sharing
# speedup vs baseline: 1.0589x; 1.0024x over previous
.LBB0_1083:
	s_and_b32 s10, s6, 3
	v_cvt_f32_ubyte0_e32 v0, s10
	v_sub_f32_e32 v0, 0xc0a00000, v0
	s_mov_b32 s0, 0xc2fc0000
	v_cmp_gt_f32_e32 vcc, s0, v0
	s_lshl_b32 s7, s6, 5
	s_and_b32 s43, s7, 0xffffff80
	v_cndmask_b32_e32 v2, 0, v248, vcc
	v_add_f32_e32 v0, v0, v2
	v_exp_f32_e32 v0, v0
	s_and_b64 s[0:1], vcc, exec
	s_cselect_b32 s0, 0xffffffc0, 0
	v_mov_b32_e32 v7, v194
	v_ldexp_f32 v0, v0, s0
	v_readlane_b32 s44, v251, 54
	v_sub_f32_e32 v19, 1.0, v0
	v_lshrrev_b32_e32 v18, 1, v7
	v_mov_b32_e32 v0, s7
	s_movk_i32 s0, 0x7f
	v_readlane_b32 s50, v251, 60
	v_readlane_b32 s51, v251, 61
	v_bfi_b32 v0, s0, v18, v0
	v_and_b32_e32 v28, 1, v7
	v_mov_b64_e32 v[2:3], s[50:51]
	v_mad_i64_i32 v[4:5], s[0:1], v0, s3, v[2:3]
	s_lshl_b32 s88, s10, 8
	v_lshl_add_u64 v[8:9], v[4:5], 0, s[88:89]
	v_lshlrev_b32_e32 v2, 7, v28
	v_mov_b32_e32 v3, v1
	v_lshl_add_u64 v[16:17], v[8:9], 0, v[2:3]
	global_load_dwordx4 v[8:11], v[16:17], off offset:3120
	global_load_dwordx4 v[12:15], v[16:17], off offset:3104
	global_load_dwordx4 v[20:23], v[16:17], off offset:3088
	global_load_dwordx4 v[24:27], v[16:17], off offset:3072
	v_bfe_u32 v6, v7, 1, 7
	v_lshlrev_b32_e32 v0, 6, v28
	v_mul_u32_u24_e32 v28, 0x2200, v28
	v_lshlrev_b32_e32 v28, 1, v28
	v_lshlrev_b32_e32 v29, 1, v6
	v_add3_u32 v30, s4, v28, v29
	v_add3_u32 v28, s4, v29, v28
	s_lshl_b32 s8, s10, 7
	s_mov_b32 s9, s89
	v_lshl_add_u64 v[4:5], v[4:5], 0, s[8:9]
	v_lshl_add_u64 v[4:5], v[4:5], 0, v[0:1]
	s_ashr_i32 s7, s6, 31
	s_lshl_b32 s11, s10, 6
	s_lshl_b64 s[0:1], s[6:7], 15
	s_add_u32 s0, s24, s0
	s_addc_u32 s1, s25, s1
	v_and_b32_e32 v66, 15, v7
	v_cmp_gt_f32_e32 vcc, s69, v19
	v_mul_u32_u24_e32 v67, 0x90, v66
	v_and_b32_e32 v122, 0x60, v18
	v_mul_u32_u24_e32 v69, 0x110, v66
	v_readfirstlane_b32 s64, v122
	s_lshr_b32 s65, s64, 1
	s_and_b32 s2, s65, 16
	s_and_b32 s66, s65, 0x60
	v_mov_b32_e32 v122, s66
	v_or_b32_e32 v125, v122, v66
	v_readlane_b32 s45, v251, 55
	v_readlane_b32 s46, v251, 56
	v_readlane_b32 s47, v251, 57
	v_readlane_b32 s48, v251, 58
	v_readlane_b32 s49, v251, 59
	v_readlane_b32 s52, v251, 62
	v_readlane_b32 s53, v251, 63
	v_readlane_b32 s54, v252, 0
	v_readlane_b32 s55, v252, 1
	v_readlane_b32 s56, v252, 2
	v_readlane_b32 s57, v252, 3
	v_readlane_b32 s58, v252, 4
	v_readlane_b32 s59, v252, 5
	s_waitcnt vmcnt(0)
	ds_write_b16 v30, v24
	ds_write_b16_d16_hi v28, v24 offset:272
	ds_write_b16 v30, v25 offset:544
	ds_write_b16_d16_hi v28, v25 offset:816
	ds_write_b16 v30, v26 offset:1088
	ds_write_b16_d16_hi v28, v26 offset:1360
	ds_write_b16 v30, v27 offset:1632
	ds_write_b16_d16_hi v28, v27 offset:1904
	ds_write_b16 v30, v20 offset:2176
	ds_write_b16_d16_hi v28, v20 offset:2448
	ds_write_b16 v30, v21 offset:2720
	ds_write_b16_d16_hi v28, v21 offset:2992
	ds_write_b16 v30, v22 offset:3264
	ds_write_b16_d16_hi v28, v22 offset:3536
	ds_write_b16 v30, v23 offset:3808
	ds_write_b16_d16_hi v28, v23 offset:4080
	ds_write_b16 v30, v12 offset:4352
	ds_write_b16_d16_hi v28, v12 offset:4624
	ds_write_b16 v30, v13 offset:4896
	ds_write_b16_d16_hi v28, v13 offset:5168
	ds_write_b16 v30, v14 offset:5440
	ds_write_b16_d16_hi v28, v14 offset:5712
	ds_write_b16 v30, v15 offset:5984
	ds_write_b16_d16_hi v28, v15 offset:6256
	ds_write_b16 v30, v8 offset:6528
	ds_write_b16_d16_hi v28, v8 offset:6800
	ds_write_b16 v30, v9 offset:7072
	ds_write_b16_d16_hi v28, v9 offset:7344
	ds_write_b16 v30, v10 offset:7616
	ds_write_b16_d16_hi v28, v10 offset:7888
	ds_write_b16 v30, v11 offset:8160
	ds_write_b16_d16_hi v28, v11 offset:8432
	global_load_dwordx4 v[8:11], v[16:17], off offset:3184
	global_load_dwordx4 v[12:15], v[16:17], off offset:3168
	global_load_dwordx4 v[20:23], v[16:17], off offset:3152
	global_load_dwordx4 v[24:27], v[16:17], off offset:3136
	s_waitcnt vmcnt(0)
	ds_write_b16 v30, v24 offset:8704
	ds_write_b16_d16_hi v28, v24 offset:8976
	ds_write_b16 v30, v25 offset:9248
	ds_write_b16_d16_hi v28, v25 offset:9520
	ds_write_b16 v30, v26 offset:9792
	ds_write_b16_d16_hi v28, v26 offset:10064
	ds_write_b16 v30, v27 offset:10336
	ds_write_b16_d16_hi v28, v27 offset:10608
	ds_write_b16 v30, v20 offset:10880
	ds_write_b16_d16_hi v28, v20 offset:11152
	ds_write_b16 v30, v21 offset:11424
	ds_write_b16_d16_hi v28, v21 offset:11696
	ds_write_b16 v30, v22 offset:11968
	ds_write_b16_d16_hi v28, v22 offset:12240
	ds_write_b16 v30, v23 offset:12512
	ds_write_b16_d16_hi v28, v23 offset:12784
	ds_write_b16 v30, v12 offset:13056
	ds_write_b16_d16_hi v28, v12 offset:13328
	ds_write_b16 v30, v13 offset:13600
	ds_write_b16_d16_hi v28, v13 offset:13872
	ds_write_b16 v30, v14 offset:14144
	ds_write_b16_d16_hi v28, v14 offset:14416
	ds_write_b16 v30, v15 offset:14688
	ds_write_b16_d16_hi v28, v15 offset:14960
	ds_write_b16 v30, v8 offset:15232
	ds_write_b16_d16_hi v28, v8 offset:15504
	ds_write_b16 v30, v9 offset:15776
	ds_write_b16_d16_hi v28, v9 offset:16048
	ds_write_b16 v30, v10 offset:16320
	ds_write_b16_d16_hi v28, v10 offset:16592
	ds_write_b16 v30, v11 offset:16864
	ds_write_b16_d16_hi v28, v11 offset:17136
	v_mul_u32_u24_e32 v8, 0x48, v6
	v_lshlrev_b32_e32 v8, 1, v8
	v_add3_u32 v21, s4, v8, v0
	global_load_dwordx4 v[8:11], v[4:5], off offset:2560
	v_lshlrev_b32_e32 v0, 8, v6
	v_bfe_u32 v20, v7, 4, 2
	v_lshlrev_b32_e32 v68, 3, v20
	v_lshlrev_b32_e32 v114, 2, v20
	v_add3_u32 v127, v69, v68, s4
	v_sub_u32_e32 v128, v66, v114
	s_waitcnt vmcnt(0)
	ds_write_b128 v21, v[8:11] offset:34816
	global_load_dwordx4 v[8:11], v[4:5], off offset:2576
	s_waitcnt vmcnt(0)
	ds_write_b128 v21, v[8:11] offset:34832
	global_load_dwordx4 v[8:11], v[4:5], off offset:2592
	s_waitcnt vmcnt(0)
	ds_write_b128 v21, v[8:11] offset:34848
	global_load_dwordx4 v[8:11], v[4:5], off offset:2608
	v_lshl_add_u64 v[4:5], s[0:1], 0, v[0:1]
	v_lshl_add_u64 v[22:23], v[4:5], 0, v[2:3]
	s_and_b64 s[0:1], vcc, exec
	s_cselect_b32 s0, 32, 0
	v_ldexp_f32 v0, v19, s0
	v_log_f32_e32 v0, v0
	s_mov_b32 s0, 0x3f317217
	s_lshl_b32 s7, s10, 9
	s_waitcnt vmcnt(0)
	ds_write_b128 v21, v[8:11] offset:34864
	global_load_dwordx4 v[2:5], v[22:23], off offset:48
	global_load_dwordx4 v[6:9], v[22:23], off offset:32
	global_load_dwordx4 v[10:13], v[22:23], off offset:16
	global_load_dwordx4 v[14:17], v[22:23], off
	s_waitcnt vmcnt(2)
	v_cvt_pk_bf16_f32 v6, v6, v7
	v_cvt_pk_bf16_f32 v7, v8, v9
	s_waitcnt vmcnt(0)
	v_cvt_pk_bf16_f32 v14, v14, v15
	v_cvt_pk_bf16_f32 v15, v16, v17
	v_cvt_pk_bf16_f32 v16, v10, v11
	v_cvt_pk_bf16_f32 v17, v12, v13
	v_cvt_pk_bf16_f32 v8, v2, v3
	v_cvt_pk_bf16_f32 v9, v4, v5
	ds_write_b128 v21, v[14:17] offset:53248
	ds_write_b128 v21, v[6:9] offset:53264
	global_load_dwordx4 v[2:5], v[22:23], off offset:112
	global_load_dwordx4 v[6:9], v[22:23], off offset:96
	global_load_dwordx4 v[10:13], v[22:23], off offset:80
	global_load_dwordx4 v[14:17], v[22:23], off offset:64
	s_waitcnt vmcnt(2)
	v_cvt_pk_bf16_f32 v6, v6, v7
	v_cvt_pk_bf16_f32 v7, v8, v9
	v_cvt_pk_bf16_f32 v8, v2, v3
	v_mul_f32_e32 v2, 0x3f317217, v0
	v_fma_f32 v2, v0, s0, -v2
	v_fmac_f32_e32 v2, 0x3377d1cf, v0
	s_mov_b32 s0, 0x7f800000
	v_fmac_f32_e32 v2, 0x3f317217, v0
	v_cmp_lt_f32_e64 s[0:1], |v0|, s0
	s_waitcnt vmcnt(0)
	v_cvt_pk_bf16_f32 v14, v14, v15
	v_cvt_pk_bf16_f32 v15, v16, v17
	v_cndmask_b32_e64 v0, v0, v2, s[0:1]
	v_cndmask_b32_e32 v2, 0, v231, vcc
	v_cmp_lt_i32_e32 vcc, v237, v235
	v_sub_f32_e32 v115, v0, v2
	v_cvt_pk_bf16_f32 v16, v10, v11
	v_cndmask_b32_e32 v0, v234, v237, vcc
	v_cmp_lt_i32_e32 vcc, v236, v235
	v_lshlrev_b32_e32 v123, 2, v0
	v_cvt_pk_bf16_f32 v17, v12, v13
	v_cndmask_b32_e32 v0, v234, v236, vcc
	v_lshlrev_b32_e32 v124, 2, v0
	v_lshlrev_b32_e32 v0, 4, v20
	v_add3_u32 v46, s4, v0, v67
	v_cvt_pk_bf16_f32 v9, v4, v5
	v_add_u32_e32 v54, 0x900, v46
	v_add_u32_e32 v62, 0x1200, v46
	ds_write_b128 v21, v[14:17] offset:53280
	ds_write_b128 v21, v[6:9] offset:53296
	s_waitcnt lgkmcnt(0)
	s_barrier
	ds_read_b128 v[2:5], v46 offset:53248
	ds_read_b128 v[6:9], v46 offset:53312
	ds_read_b128 v[10:13], v46 offset:55552
	ds_read_b128 v[14:17], v46 offset:55616
	ds_read_b128 v[18:21], v46 offset:57856
	ds_read_b128 v[22:25], v46 offset:57920
	ds_read_b128 v[26:29], v46 offset:60160
	ds_read_b128 v[30:33], v46 offset:60224
	ds_read_b128 v[34:37], v46 offset:62464
	ds_read_b128 v[38:41], v46 offset:62528
	ds_read_b128 v[42:45], v46 offset:64768
	ds_read_b128 v[46:49], v46 offset:64832
	ds_read_b128 v[50:53], v54 offset:64768
	ds_read_b128 v[54:57], v54 offset:64832
	ds_read_b128 v[58:61], v62 offset:64768
	ds_read_b128 v[62:65], v62 offset:64832
	s_add_u32 s0, s5, s7
	s_addc_u32 s1, s20, 0
	s_add_u32 s12, s21, s7
	s_addc_u32 s13, s39, 0
	v_lshl_add_u64 v[116:117], s[0:1], 0, v[0:1]
	v_lshl_add_u64 v[118:119], s[12:13], 0, v[0:1]
	v_add3_u32 v126, v67, v0, s42
	s_mov_b64 s[0:1], -1
	s_lshl_b32 s88, s11, 1
	v_lshlrev_b32_e32 v0, 1, v68
	s_lshl_b32 s12, s8, 1

.LBB0_1085:
	ds_read_b128 v[106:109], v129
	ds_read_b128 v[130:133], v129 offset:64
	s_add_i32 s2, s2, 32
	s_waitcnt vmcnt(1) lgkmcnt(1)
	v_mfma_f32_16x16x32_bf16 v[106:109], v[106:109], v[102:105], 0
	ds_read_b128 v[134:137], v129 offset:2368
	s_waitcnt vmcnt(0) lgkmcnt(1)
	v_mfma_f32_16x16x32_bf16 v[106:109], v[130:133], v[70:73], v[106:109]
	ds_read_b128 v[130:133], v129 offset:2304
	v_add_u32_e32 v129, 0x1200, v129
	s_waitcnt lgkmcnt(0)
	v_mfma_f32_16x16x32_bf16 v[130:133], v[130:133], v[102:105], 0
	s_nop 3
	v_mul_f32_e32 v106, 0x3e000000, v106
	v_mul_f32_e32 v107, 0x3e000000, v107
	v_pk_mul_f32 v[108:109], v[108:109], s[18:19] op_sel_hi:[1,0]
	v_mfma_f32_16x16x32_bf16 v[130:133], v[134:137], v[70:73], v[130:133]
	v_add_u32_e32 v135, v122, v112
	v_cvt_f32_u32_e32 v137, v135
	v_add_u32_e32 v136, -16, v135
	v_cmp_lt_i32_e32 vcc, -1, v135
	v_add_u32_e32 v134, s2, v114
	v_mul_f32_e32 v137, v115, v137
	v_mul_f32_e32 v137, 0x3fb8aa3b, v137
	v_exp_f32_e32 v137, v137
	v_subrev_u32_e32 v112, 32, v112
	v_mul_f32_e32 v106, v106, v137
	v_cndmask_b32_e32 v137, 0, v106, vcc
	v_mul_f32_e32 v106, 0x3e000000, v130
	v_cvt_f32_u32_e32 v130, v136
	v_cmp_lt_i32_e32 vcc, 15, v135
	v_mul_f32_e32 v130, v115, v130
	v_mul_f32_e32 v130, 0x3fb8aa3b, v130
	v_exp_f32_e32 v130, v130
	s_nop 0
	v_mul_f32_e32 v106, v130, v106
	v_cndmask_b32_e32 v136, 0, v106, vcc
	v_add_u32_e32 v106, -1, v135
	v_subrev_u32_e32 v130, 17, v135
	v_cvt_f32_u32_e32 v135, v106
	v_cmp_lt_i32_e32 vcc, -1, v106
	v_mul_f32_e32 v135, v115, v135
	v_mul_f32_e32 v135, 0x3fb8aa3b, v135
	v_exp_f32_e32 v135, v135
	s_nop 0
	v_mul_f32_e32 v107, v107, v135
	v_cndmask_b32_e32 v135, 0, v107, vcc
	v_cvt_f32_u32_e32 v107, v130
	v_cmp_lt_i32_e32 vcc, 15, v106
	v_mul_f32_e32 v106, 0x3e000000, v131
	v_mul_f32_e32 v107, v115, v107
	v_mul_f32_e32 v107, 0x3fb8aa3b, v107
	v_exp_f32_e32 v107, v107
	s_nop 0
	v_mul_f32_e32 v106, v107, v106
	v_or_b32_e32 v107, 2, v134
	v_cndmask_b32_e32 v138, 0, v106, vcc
	v_or_b32_e32 v106, 3, v134
	v_sub_u32_e32 v134, v110, v107
	v_add_u32_e32 v107, -16, v134
	v_cvt_f32_u32_e32 v107, v107
	v_sub_u32_e32 v131, v111, v106
	v_cvt_f32_u32_e32 v106, v134
	v_add_u32_e32 v139, -16, v131
	v_mul_f32_e32 v107, v115, v107
	v_mul_f32_e32 v107, 0x3fb8aa3b, v107
	v_exp_f32_e32 v130, v107
	v_cvt_f32_u32_e32 v107, v131
	v_cmp_lt_i32_e32 vcc, -1, v131
	v_cmp_lt_i32_e64 s[8:9], 15, v131
	v_cvt_f32_u32_e32 v131, v139
	v_mul_f32_e32 v106, v115, v106
	v_mul_f32_e32 v107, v115, v107
	v_mul_f32_e32 v106, 0x3fb8aa3b, v106
	v_mul_f32_e32 v107, 0x3fb8aa3b, v107
	v_mul_f32_e32 v131, v115, v131
	v_exp_f32_e32 v106, v106
	v_exp_f32_e32 v107, v107
	v_mul_f32_e32 v131, 0x3fb8aa3b, v131
	v_exp_f32_e32 v131, v131
	v_cmp_lt_i32_e64 s[10:11], 15, v134
	v_pk_mul_f32 v[108:109], v[108:109], v[106:107]
	v_pk_mul_f32 v[106:107], v[132:133], s[18:19] op_sel_hi:[1,0]
	v_cmp_lt_i32_e64 s[0:1], -1, v134
	v_pk_mul_f32 v[130:131], v[130:131], v[106:107]
	v_cvt_pk_bf16_f32 v107, v108, v109
	v_cvt_pk_bf16_f32 v109, v130, v131
	v_cndmask_b32_e64 v130, 0, v109, s[10:11]
	v_lshrrev_b32_e32 v109, 16, v109
	v_cndmask_b32_e64 v109, 0, v109, s[8:9]
	v_perm_b32 v109, v109, v130, s19
	ds_read2_b64 v[130:133], v113 offset1:4
	v_cndmask_b32_e64 v108, 0, v107, s[0:1]
	v_lshrrev_b32_e32 v107, 16, v107
	v_cndmask_b32_e32 v107, 0, v107, vcc
	v_cvt_pk_bf16_f32 v106, v137, v135
	v_perm_b32 v107, v107, v108, s19
	v_cvt_pk_bf16_f32 v108, v136, v138
	v_cmp_eq_u32_e32 vcc, s2, v122
	s_or_b64 s[16:17], vcc, s[16:17]
	s_waitcnt lgkmcnt(0)
	v_mfma_f32_16x16x32_bf16 v[98:101], v[130:133], v[106:109], v[98:101]
	v_add_u32_e32 v130, 0x1000, v113
	ds_read2_b64 v[130:133], v130 offset0:32 offset1:36
	s_waitcnt lgkmcnt(0)
	v_mfma_f32_16x16x32_bf16 v[82:85], v[130:133], v[106:109], v[82:85]
	v_add_u32_e32 v130, 0x2000, v113
	ds_read2_b64 v[130:133], v130 offset0:64 offset1:68
	s_waitcnt lgkmcnt(0)
	v_mfma_f32_16x16x32_bf16 v[74:77], v[130:133], v[106:109], v[74:77]
	v_add_u32_e32 v130, 0x3000, v113
	ds_read2_b64 v[130:133], v130 offset0:96 offset1:100
	s_waitcnt lgkmcnt(0)
	v_mfma_f32_16x16x32_bf16 v[66:69], v[130:133], v[106:109], v[66:69]
	v_add_u32_e32 v130, 0x4000, v113
	ds_read2_b64 v[130:133], v130 offset0:128 offset1:132
	s_waitcnt lgkmcnt(0)
	v_mfma_f32_16x16x32_bf16 v[90:93], v[130:133], v[106:109], v[90:93]
	v_add_u32_e32 v130, 0x5000, v113
	ds_read2_b64 v[130:133], v130 offset0:160 offset1:164
	s_waitcnt lgkmcnt(0)
	v_mfma_f32_16x16x32_bf16 v[94:97], v[130:133], v[106:109], v[94:97]
	v_add_u32_e32 v130, 0x6000, v113
	ds_read2_b64 v[130:133], v130 offset0:192 offset1:196
	s_waitcnt lgkmcnt(0)
	v_mfma_f32_16x16x32_bf16 v[86:89], v[130:133], v[106:109], v[86:89]
	v_add_u32_e32 v130, 0x7000, v113
	ds_read2_b64 v[130:133], v130 offset0:224 offset1:228
	v_add_u32_e32 v113, 64, v113
	s_waitcnt lgkmcnt(0)
	v_mfma_f32_16x16x32_bf16 v[78:81], v[130:133], v[106:109], v[78:81]
	s_andn2_b64 exec, exec, s[16:17]
	s_cbranch_execnz .LBB0_1085
	s_or_b64 exec, exec, s[16:17]
	v_add_u32_e32 v106, 1, v110
	v_cvt_f32_u32_e32 v107, v106
	v_lshlrev_b32_e32 v106, 16, v102
	s_mov_b32 s13, s89
	s_brev_b32 s0, 60
	v_mul_f32_e32 v107, v115, v107
	v_mul_f32_e32 v107, 0x3fb8aa3b, v107
	v_exp_f32_e32 v108, v107
	v_and_b32_e32 v107, 0xffff0000, v102
	v_lshlrev_b32_e32 v102, 16, v103
	v_and_b32_e32 v103, 0xffff0000, v103
	v_pk_mul_f32 v[102:103], v[108:109], v[102:103] op_sel_hi:[0,1]
	v_cvt_pk_bf16_f32 v131, v102, v103
	v_lshlrev_b32_e32 v102, 16, v104
	v_and_b32_e32 v103, 0xffff0000, v104
	v_pk_mul_f32 v[102:103], v[108:109], v[102:103] op_sel_hi:[0,1]
	v_cvt_pk_bf16_f32 v132, v102, v103
	v_lshlrev_b32_e32 v102, 16, v105
	v_and_b32_e32 v103, 0xffff0000, v105
	v_pk_mul_f32 v[102:103], v[108:109], v[102:103] op_sel_hi:[0,1]
	v_cvt_pk_bf16_f32 v133, v102, v103
	v_lshlrev_b32_e32 v102, 16, v70
	v_and_b32_e32 v103, 0xffff0000, v70
	v_lshlrev_b32_e32 v70, 16, v71
	v_and_b32_e32 v71, 0xffff0000, v71
	v_pk_mul_f32 v[106:107], v[108:109], v[106:107] op_sel_hi:[0,1]
	v_pk_mul_f32 v[70:71], v[108:109], v[70:71] op_sel_hi:[0,1]
	v_cvt_pk_bf16_f32 v130, v106, v107
	v_cvt_pk_bf16_f32 v135, v70, v71
	v_lshlrev_b32_e32 v70, 16, v72
	v_and_b32_e32 v71, 0xffff0000, v72
	v_pk_mul_f32 v[70:71], v[108:109], v[70:71] op_sel_hi:[0,1]
	v_mfma_f32_16x16x32_bf16 v[98:101], v[2:5], v[130:133], v[98:101]
	v_cvt_pk_bf16_f32 v136, v70, v71
	v_lshlrev_b32_e32 v70, 16, v73
	v_and_b32_e32 v71, 0xffff0000, v73
	v_mfma_f32_16x16x32_bf16 v[66:69], v[26:29], v[130:133], v[66:69]
	v_mul_f32_e64 v102, v108, v102
	v_mul_f32_e64 v103, v108, v103
	v_pk_mul_f32 v[70:71], v[108:109], v[70:71] op_sel_hi:[0,1]
	v_cvt_pk_bf16_f32 v134, v102, v103
	v_cvt_pk_bf16_f32 v137, v70, v71
	v_mfma_f32_16x16x32_bf16 v[70:73], v[10:13], v[130:133], v[82:85]
	s_sub_i32 s67, 0x70, s65
	s_and_b32 s2, s67, 16
	s_and_b32 s66, s67, 0x60
	v_mov_b32_e32 v122, s66
	v_and_b32_e32 v125, 15, v125
	v_or_b32_e32 v125, v122, v125
	v_mfma_f32_16x16x32_bf16 v[110:113], v[6:9], v[134:137], v[98:101]
	v_mfma_f32_16x16x32_bf16 v[98:101], v[30:33], v[134:137], v[66:69]
	v_mfma_f32_16x16x32_bf16 v[66:69], v[34:37], v[130:133], v[90:93]
	s_nop 5
	v_mul_f32_e32 v129, v111, v111
	v_fmac_f32_e32 v129, v110, v110
	v_fmac_f32_e32 v129, v112, v112
	v_mfma_f32_16x16x32_bf16 v[82:85], v[38:41], v[134:137], v[66:69]
	v_fmac_f32_e32 v129, v113, v113
	v_mfma_f32_16x16x32_bf16 v[66:69], v[42:45], v[130:133], v[94:97]
	v_mfma_f32_16x16x32_bf16 v[106:109], v[14:17], v[134:137], v[70:73]
	v_mfma_f32_16x16x32_bf16 v[70:73], v[18:21], v[130:133], v[74:77]
	v_mfma_f32_16x16x32_bf16 v[74:77], v[46:49], v[134:137], v[66:69]
	s_nop 5
	v_fmac_f32_e32 v129, v106, v106
	v_fmac_f32_e32 v129, v107, v107
	v_fmac_f32_e32 v129, v108, v108
	v_mfma_f32_16x16x32_bf16 v[66:69], v[50:53], v[130:133], v[86:89]
	v_fmac_f32_e32 v129, v109, v109
	v_mfma_f32_16x16x32_bf16 v[102:105], v[22:25], v[134:137], v[70:73]
	s_nop 2
	v_add_f32_e32 v70, 0, v110
	v_add_f32_e32 v86, v111, v70
	v_mfma_f32_16x16x32_bf16 v[70:73], v[54:57], v[134:137], v[66:69]
	s_nop 1
	v_fmac_f32_e32 v129, v102, v102
	v_fmac_f32_e32 v129, v103, v103
	v_fmac_f32_e32 v129, v104, v104
	v_add_f32_e32 v66, v112, v86
	v_add_f32_e32 v86, v113, v66
	v_mfma_f32_16x16x32_bf16 v[66:69], v[58:61], v[130:133], v[78:81]
	v_fmac_f32_e32 v129, v105, v105
	v_fmac_f32_e32 v129, v98, v98
	v_fmac_f32_e32 v129, v99, v99
	v_add_f32_e32 v78, v86, v106
	v_add_f32_e32 v78, v107, v78
	v_add_f32_e32 v78, v108, v78
	v_add_f32_e32 v78, v109, v78
	v_add_f32_e32 v78, v78, v102
	v_add_f32_e32 v78, v103, v78
	v_add_f32_e32 v78, v104, v78
	v_add_f32_e32 v78, v105, v78
	v_add_f32_e32 v78, v78, v98
	v_add_f32_e32 v90, v99, v78
	v_lshl_add_u64 v[78:79], v[120:121], 0, s[12:13]
	v_lshlrev_b32_e32 v80, 1, v114
	v_mov_b32_e32 v81, v1
	v_lshl_add_u64 v[86:87], v[78:79], 0, v[80:81]
	v_add_co_u32_e32 v96, vcc, s68, v86
	v_add_f32_e32 v78, v100, v90
	s_nop 0
	v_addc_co_u32_e32 v97, vcc, 0, v87, vcc
	global_load_dwordx2 v[88:89], v[96:97], off
	v_add_f32_e32 v78, v101, v78
	v_add_f32_e32 v78, v78, v82
	v_add_f32_e32 v78, v83, v78
	v_add_f32_e32 v78, v84, v78
	v_add_f32_e32 v90, v85, v78
	global_load_dwordx4 v[78:81], v[116:117], off
	global_load_dwordx4 v[92:95], v[118:119], off
	v_fmac_f32_e32 v129, v100, v100
	v_fmac_f32_e32 v129, v101, v101
	v_fmac_f32_e32 v129, v82, v82
	v_fmac_f32_e32 v129, v83, v83
	v_add_f32_e32 v120, v90, v74
	v_pk_mov_b32 v[90:91], v[84:85], v[74:75] op_sel:[1,0]
	v_fmac_f32_e32 v129, v84, v84
	v_pk_mul_f32 v[90:91], v[90:91], v[90:91]
	v_mfma_f32_16x16x32_bf16 v[66:69], v[62:65], v[134:137], v[66:69]
	v_add_f32_e32 v90, v90, v129
	v_add_f32_e32 v129, v90, v91
	v_add_f32_e32 v90, v75, v120
	v_add_f32_e32 v130, v76, v90
	v_pk_mul_f32 v[90:91], v[76:77], v[76:77]
	v_pk_mul_f32 v[120:121], v[74:75], v[74:75]
	s_nop 0
	v_add_f32_e32 v91, v121, v129
	v_add_f32_e32 v120, v90, v91
	v_add_f32_e32 v90, v77, v130
	v_add_f32_e32 v121, v90, v70
	v_pk_mov_b32 v[90:91], v[76:77], v[70:71] op_sel:[1,0]
	s_nop 0
	v_pk_mul_f32 v[90:91], v[90:91], v[90:91]
	s_nop 0
	v_add_f32_e32 v90, v90, v120
	v_add_f32_e32 v129, v90, v91
	v_add_f32_e32 v90, v71, v121
	v_add_f32_e32 v130, v72, v90
	v_pk_mul_f32 v[90:91], v[72:73], v[72:73]
	v_pk_mul_f32 v[120:121], v[70:71], v[70:71]
	s_nop 0
	v_add_f32_e32 v91, v121, v129
	v_add_f32_e32 v120, v90, v91
	v_add_f32_e32 v90, v73, v130
	v_add_f32_e32 v121, v90, v66
	v_pk_mov_b32 v[90:91], v[72:73], v[66:67] op_sel:[1,0]
	v_pk_mul_f32 v[130:131], v[66:67], v[66:67]
	v_pk_mul_f32 v[90:91], v[90:91], v[90:91]
	s_waitcnt vmcnt(2)
	v_lshlrev_b32_e32 v130, 16, v88
	v_add_f32_e32 v90, v90, v120
	v_add_f32_e32 v90, v90, v91
	v_add_f32_e32 v91, v67, v121
	v_pk_mul_f32 v[120:121], v[68:69], v[68:69]
	v_add_f32_e32 v90, v131, v90
	v_add_f32_e32 v91, v68, v91
	v_add_f32_e32 v120, v120, v90
	v_mul_f32_e32 v90, v69, v69
	v_mov_b32_e32 v121, v69
	v_pk_add_f32 v[90:91], v[120:121], v[90:91]
	ds_bpermute_b32 v121, v123, v91
	ds_bpermute_b32 v120, v123, v90
	v_and_b32_e32 v131, 0xffff0000, v88
	v_mul_f32_e32 v88, 0xbfb8aa3b, v130
	v_exp_f32_e32 v133, v88
	v_mul_f32_e32 v88, 0xbfb8aa3b, v131
	s_waitcnt lgkmcnt(0)
	v_pk_add_f32 v[90:91], v[90:91], v[120:121]
	ds_bpermute_b32 v121, v124, v91
	ds_bpermute_b32 v120, v124, v90
	v_exp_f32_e32 v134, v88
	s_waitcnt lgkmcnt(0)
	v_pk_add_f32 v[90:91], v[90:91], v[120:121]
	s_nop 0
	v_pk_mul_f32 v[90:91], v[90:91], s[0:1] op_sel_hi:[1,0]
	s_mov_b64 s[0:1], 0x1000
	v_fma_f32 v120, -v91, v91, v90
	v_max_f32_e32 v120, 0, v120
	v_add_f32_e32 v120, 0x358637bd, v120
	v_mul_f32_e32 v121, 0x4b800000, v120
	v_cmp_gt_f32_e32 vcc, s69, v120
	v_pk_add_f32 v[110:111], v[110:111], v[90:91] op_sel:[0,1] neg_lo:[0,1] neg_hi:[0,1]
	v_lshl_add_u64 v[86:87], v[86:87], 0, s[0:1]
	v_cndmask_b32_e32 v120, v120, v121, vcc
	v_rsq_f32_e32 v129, v120
	global_load_dwordx2 v[120:121], v[86:87], off offset:32
	v_pk_add_f32 v[112:113], v[112:113], v[90:91] op_sel:[0,1] neg_lo:[0,1] neg_hi:[0,1]
	v_pk_add_f32 v[106:107], v[106:107], v[90:91] op_sel:[0,1] neg_lo:[0,1] neg_hi:[0,1]
	v_mul_f32_e32 v132, 0x45800000, v129
	v_cndmask_b32_e32 v88, v129, v132, vcc
	v_add_f32_e32 v129, 1.0, v133
	v_rcp_f32_e32 v132, v129
	v_add_f32_e32 v129, 1.0, v134
	v_rcp_f32_e32 v133, v129
	v_pk_mul_f32 v[110:111], v[110:111], v[88:89] op_sel_hi:[1,0]
	v_pk_add_f32 v[102:103], v[102:103], v[90:91] op_sel:[0,1] neg_lo:[0,1] neg_hi:[0,1]
	s_waitcnt vmcnt(1)
	v_pk_fma_f32 v[78:79], v[78:79], v[110:111], v[92:93]
	v_pk_mul_f32 v[92:93], v[132:133], v[130:131]
	v_pk_add_f32 v[104:105], v[104:105], v[90:91] op_sel:[0,1] neg_lo:[0,1] neg_hi:[0,1]
	v_pk_mul_f32 v[78:79], v[92:93], v[78:79]
	v_lshlrev_b32_e32 v92, 16, v89
	v_and_b32_e32 v93, 0xffff0000, v89
	v_mul_f32_e32 v89, 0xbfb8aa3b, v92
	v_exp_f32_e32 v89, v89
	v_mul_f32_e32 v110, 0xbfb8aa3b, v93
	v_exp_f32_e32 v111, v110
	v_cvt_pk_bf16_f32 v78, v78, v79
	v_add_f32_e32 v79, 1.0, v89
	v_rcp_f32_e32 v110, v79
	v_add_f32_e32 v79, 1.0, v111
	v_rcp_f32_e32 v111, v79
	v_pk_mul_f32 v[112:113], v[112:113], v[88:89] op_sel_hi:[1,0]
	v_pk_add_f32 v[98:99], v[98:99], v[90:91] op_sel:[0,1] neg_lo:[0,1] neg_hi:[0,1]
	v_pk_fma_f32 v[80:81], v[80:81], v[112:113], v[94:95]
	v_pk_mul_f32 v[92:93], v[110:111], v[92:93]
	v_pk_add_f32 v[100:101], v[100:101], v[90:91] op_sel:[0,1] neg_lo:[0,1] neg_hi:[0,1]
	v_pk_mul_f32 v[80:81], v[92:93], v[80:81]
	v_pk_add_f32 v[82:83], v[82:83], v[90:91] op_sel:[0,1] neg_lo:[0,1] neg_hi:[0,1]
	v_cvt_pk_bf16_f32 v79, v80, v81
	global_store_dwordx2 v[96:97], v[78:79], off
	global_load_dwordx4 v[78:81], v[116:117], off offset:64
	s_nop 0
	global_load_dwordx4 v[92:95], v[118:119], off offset:64
	v_pk_add_f32 v[84:85], v[84:85], v[90:91] op_sel:[0,1] neg_lo:[0,1] neg_hi:[0,1]
	v_pk_add_f32 v[74:75], v[74:75], v[90:91] op_sel:[0,1] neg_lo:[0,1] neg_hi:[0,1]
	v_pk_add_f32 v[76:77], v[76:77], v[90:91] op_sel:[0,1] neg_lo:[0,1] neg_hi:[0,1]
	v_pk_add_f32 v[70:71], v[70:71], v[90:91] op_sel:[0,1] neg_lo:[0,1] neg_hi:[0,1]
	v_pk_add_f32 v[72:73], v[72:73], v[90:91] op_sel:[0,1] neg_lo:[0,1] neg_hi:[0,1]
	v_pk_add_f32 v[66:67], v[66:67], v[90:91] op_sel:[0,1] neg_lo:[0,1] neg_hi:[0,1]
	v_pk_add_f32 v[68:69], v[68:69], v[90:91] op_sel:[0,1] neg_lo:[0,1] neg_hi:[0,1]
	s_mov_b64 s[0:1], 0
	s_and_b64 vcc, exec, s[14:15]
	s_waitcnt vmcnt(3)
	v_lshlrev_b32_e32 v96, 16, v120
	v_and_b32_e32 v97, 0xffff0000, v120
	v_mul_f32_e32 v89, 0xbfb8aa3b, v96
	v_exp_f32_e32 v89, v89
	v_mul_f32_e32 v110, 0xbfb8aa3b, v97
	v_exp_f32_e32 v113, v110
	global_load_dwordx2 v[110:111], v[86:87], off offset:64
	v_add_f32_e32 v89, 1.0, v89
	v_rcp_f32_e32 v112, v89
	v_add_f32_e32 v89, 1.0, v113
	v_rcp_f32_e32 v113, v89
	v_pk_mul_f32 v[106:107], v[106:107], v[88:89] op_sel_hi:[1,0]
	s_waitcnt vmcnt(1)
	v_pk_fma_f32 v[78:79], v[106:107], v[78:79], v[92:93]
	v_pk_mul_f32 v[92:93], v[112:113], v[96:97]
	v_pk_add_f32 v[106:107], v[108:109], v[90:91] op_sel:[0,1] neg_lo:[0,1] neg_hi:[0,1]
	v_pk_mul_f32 v[78:79], v[92:93], v[78:79]
	v_lshlrev_b32_e32 v92, 16, v121
	v_and_b32_e32 v93, 0xffff0000, v121
	v_mul_f32_e32 v89, 0xbfb8aa3b, v92
	v_exp_f32_e32 v89, v89
	v_mul_f32_e32 v96, 0xbfb8aa3b, v93
	v_exp_f32_e32 v97, v96
	v_cvt_pk_bf16_f32 v78, v78, v79
	v_add_f32_e32 v79, 1.0, v89
	v_rcp_f32_e32 v96, v79
	v_add_f32_e32 v79, 1.0, v97
	v_rcp_f32_e32 v97, v79
	v_pk_mul_f32 v[106:107], v[106:107], v[88:89] op_sel_hi:[1,0]
	v_pk_mul_f32 v[92:93], v[96:97], v[92:93]
	v_pk_fma_f32 v[80:81], v[106:107], v[80:81], v[94:95]
	s_waitcnt vmcnt(0)
	v_lshlrev_b32_e32 v106, 16, v110
	v_pk_mul_f32 v[80:81], v[92:93], v[80:81]
	v_and_b32_e32 v107, 0xffff0000, v110
	v_cvt_pk_bf16_f32 v79, v80, v81
	global_store_dwordx2 v[86:87], v[78:79], off offset:32
	global_load_dwordx4 v[78:81], v[116:117], off offset:128
	s_nop 0
	global_load_dwordx4 v[92:95], v[118:119], off offset:128
	global_load_dwordx2 v[96:97], v[86:87], off offset:96
	v_lshlrev_b32_e32 v108, 16, v111
	v_and_b32_e32 v109, 0xffff0000, v111
	v_mul_f32_e32 v89, 0xbfb8aa3b, v106
	v_mul_f32_e32 v110, 0xbfb8aa3b, v107
	v_mul_f32_e32 v111, 0xbfb8aa3b, v108
	v_mul_f32_e32 v112, 0xbfb8aa3b, v109
	v_exp_f32_e32 v89, v89
	v_exp_f32_e32 v110, v110
	v_exp_f32_e32 v111, v111
	v_exp_f32_e32 v112, v112
	v_add_f32_e32 v89, 1.0, v89
	v_add_f32_e32 v113, 1.0, v110
	v_add_f32_e32 v120, 1.0, v111
	v_add_f32_e32 v121, 1.0, v112
	v_rcp_f32_e32 v110, v89
	v_rcp_f32_e32 v111, v113
	v_rcp_f32_e32 v112, v120
	v_rcp_f32_e32 v113, v121
	v_pk_mul_f32 v[102:103], v[102:103], v[88:89] op_sel_hi:[1,0]
	v_pk_mul_f32 v[104:105], v[104:105], v[88:89] op_sel_hi:[1,0]
	v_pk_mul_f32 v[106:107], v[110:111], v[106:107]
	v_pk_mul_f32 v[108:109], v[112:113], v[108:109]
	s_waitcnt vmcnt(1)
	v_pk_fma_f32 v[78:79], v[102:103], v[78:79], v[92:93]
	v_pk_fma_f32 v[80:81], v[104:105], v[80:81], v[94:95]
	v_pk_mul_f32 v[78:79], v[106:107], v[78:79]
	v_pk_mul_f32 v[80:81], v[108:109], v[80:81]
	v_cvt_pk_bf16_f32 v78, v78, v79
	v_cvt_pk_bf16_f32 v79, v80, v81
	global_store_dwordx2 v[86:87], v[78:79], off offset:64
	global_load_dwordx4 v[78:81], v[116:117], off offset:192
	s_nop 0
	global_load_dwordx4 v[92:95], v[118:119], off offset:192
	global_load_dwordx2 v[102:103], v[86:87], off offset:128
	s_waitcnt vmcnt(4)
	v_lshlrev_b32_e32 v104, 16, v96
	v_and_b32_e32 v105, 0xffff0000, v96
	v_lshlrev_b32_e32 v96, 16, v97
	v_and_b32_e32 v97, 0xffff0000, v97
	v_mul_f32_e32 v89, 0xbfb8aa3b, v104
	v_mul_f32_e32 v106, 0xbfb8aa3b, v105
	v_mul_f32_e32 v107, 0xbfb8aa3b, v96
	v_mul_f32_e32 v108, 0xbfb8aa3b, v97
	v_exp_f32_e32 v89, v89
	v_exp_f32_e32 v106, v106
	v_exp_f32_e32 v107, v107
	v_exp_f32_e32 v108, v108
	v_add_f32_e32 v89, 1.0, v89
	v_add_f32_e32 v109, 1.0, v106
	v_add_f32_e32 v110, 1.0, v107
	v_add_f32_e32 v111, 1.0, v108
	v_rcp_f32_e32 v106, v89
	v_rcp_f32_e32 v107, v109
	v_rcp_f32_e32 v108, v110
	v_rcp_f32_e32 v109, v111
	v_pk_mul_f32 v[98:99], v[98:99], v[88:89] op_sel_hi:[1,0]
	v_pk_mul_f32 v[100:101], v[100:101], v[88:89] op_sel_hi:[1,0]
	v_pk_mul_f32 v[104:105], v[106:107], v[104:105]
	v_pk_mul_f32 v[96:97], v[108:109], v[96:97]
	s_waitcnt vmcnt(1)
	v_pk_fma_f32 v[78:79], v[98:99], v[78:79], v[92:93]
	v_pk_fma_f32 v[80:81], v[100:101], v[80:81], v[94:95]
	v_pk_mul_f32 v[78:79], v[104:105], v[78:79]
	v_pk_mul_f32 v[80:81], v[96:97], v[80:81]
	v_cvt_pk_bf16_f32 v78, v78, v79
	v_cvt_pk_bf16_f32 v79, v80, v81
	global_store_dwordx2 v[86:87], v[78:79], off offset:96
	global_load_dwordx4 v[78:81], v[116:117], off offset:256
	s_nop 0
	global_load_dwordx4 v[92:95], v[118:119], off offset:256
	global_load_dwordx2 v[96:97], v[86:87], off offset:160
	s_waitcnt vmcnt(4)
	v_lshlrev_b32_e32 v98, 16, v102
	v_and_b32_e32 v99, 0xffff0000, v102
	v_lshlrev_b32_e32 v100, 16, v103
	v_and_b32_e32 v101, 0xffff0000, v103
	v_mul_f32_e32 v89, 0xbfb8aa3b, v98
	v_mul_f32_e32 v102, 0xbfb8aa3b, v99
	v_mul_f32_e32 v103, 0xbfb8aa3b, v100
	v_mul_f32_e32 v104, 0xbfb8aa3b, v101
	v_exp_f32_e32 v89, v89
	v_exp_f32_e32 v102, v102
	v_exp_f32_e32 v103, v103
	v_exp_f32_e32 v104, v104
	v_add_f32_e32 v89, 1.0, v89
	v_add_f32_e32 v105, 1.0, v102
	v_add_f32_e32 v106, 1.0, v103
	v_add_f32_e32 v107, 1.0, v104
	v_rcp_f32_e32 v102, v89
	v_rcp_f32_e32 v103, v105
	v_rcp_f32_e32 v104, v106
	v_rcp_f32_e32 v105, v107
	v_pk_mul_f32 v[82:83], v[82:83], v[88:89] op_sel_hi:[1,0]
	v_pk_mul_f32 v[84:85], v[84:85], v[88:89] op_sel_hi:[1,0]
	v_pk_mul_f32 v[98:99], v[102:103], v[98:99]
	v_pk_mul_f32 v[100:101], v[104:105], v[100:101]
	s_waitcnt vmcnt(1)
	v_pk_fma_f32 v[78:79], v[82:83], v[78:79], v[92:93]
	v_pk_fma_f32 v[80:81], v[84:85], v[80:81], v[94:95]
	v_pk_mul_f32 v[78:79], v[98:99], v[78:79]
	v_pk_mul_f32 v[80:81], v[100:101], v[80:81]
	v_cvt_pk_bf16_f32 v78, v78, v79
	v_cvt_pk_bf16_f32 v79, v80, v81
	global_store_dwordx2 v[86:87], v[78:79], off offset:128
	global_load_dwordx4 v[78:81], v[116:117], off offset:320
	s_nop 0
	global_load_dwordx4 v[92:95], v[118:119], off offset:320
	global_load_dwordx2 v[82:83], v[86:87], off offset:192
	s_waitcnt vmcnt(4)
	v_lshlrev_b32_e32 v84, 16, v96
	v_and_b32_e32 v85, 0xffff0000, v96
	v_lshlrev_b32_e32 v96, 16, v97
	v_and_b32_e32 v97, 0xffff0000, v97
	v_mul_f32_e32 v89, 0xbfb8aa3b, v84
	v_mul_f32_e32 v98, 0xbfb8aa3b, v85
	v_mul_f32_e32 v99, 0xbfb8aa3b, v96
	v_mul_f32_e32 v100, 0xbfb8aa3b, v97
	v_exp_f32_e32 v89, v89
	v_exp_f32_e32 v98, v98
	v_exp_f32_e32 v99, v99
	v_exp_f32_e32 v100, v100
	v_add_f32_e32 v89, 1.0, v89
	v_add_f32_e32 v101, 1.0, v98
	v_add_f32_e32 v102, 1.0, v99
	v_add_f32_e32 v103, 1.0, v100
	v_rcp_f32_e32 v98, v89
	v_rcp_f32_e32 v99, v101
	v_rcp_f32_e32 v100, v102
	v_rcp_f32_e32 v101, v103
	v_pk_mul_f32 v[74:75], v[74:75], v[88:89] op_sel_hi:[1,0]
	v_pk_mul_f32 v[76:77], v[76:77], v[88:89] op_sel_hi:[1,0]
	v_pk_mul_f32 v[84:85], v[98:99], v[84:85]
	v_pk_mul_f32 v[96:97], v[100:101], v[96:97]
	s_waitcnt vmcnt(1)
	v_pk_fma_f32 v[74:75], v[74:75], v[78:79], v[92:93]
	v_pk_fma_f32 v[76:77], v[76:77], v[80:81], v[94:95]
	v_pk_mul_f32 v[74:75], v[84:85], v[74:75]
	v_pk_mul_f32 v[76:77], v[96:97], v[76:77]
	v_cvt_pk_bf16_f32 v74, v74, v75
	v_cvt_pk_bf16_f32 v75, v76, v77
	global_store_dwordx2 v[86:87], v[74:75], off offset:160
	global_load_dwordx4 v[74:77], v[116:117], off offset:384
	s_nop 0
	global_load_dwordx4 v[78:81], v[118:119], off offset:384
	global_load_dwordx2 v[84:85], v[86:87], off offset:224
	s_waitcnt vmcnt(4)
	v_lshlrev_b32_e32 v92, 16, v82
	v_and_b32_e32 v93, 0xffff0000, v82
	v_lshlrev_b32_e32 v82, 16, v83
	v_and_b32_e32 v83, 0xffff0000, v83
	v_mul_f32_e32 v89, 0xbfb8aa3b, v92
	v_mul_f32_e32 v94, 0xbfb8aa3b, v93
	v_mul_f32_e32 v95, 0xbfb8aa3b, v82
	v_mul_f32_e32 v96, 0xbfb8aa3b, v83
	v_exp_f32_e32 v89, v89
	v_exp_f32_e32 v94, v94
	v_exp_f32_e32 v95, v95
	v_exp_f32_e32 v96, v96
	v_add_f32_e32 v89, 1.0, v89
	v_add_f32_e32 v97, 1.0, v94
	v_add_f32_e32 v98, 1.0, v95
	v_add_f32_e32 v99, 1.0, v96
	v_rcp_f32_e32 v94, v89
	v_rcp_f32_e32 v95, v97
	v_rcp_f32_e32 v96, v98
	v_rcp_f32_e32 v97, v99
	v_pk_mul_f32 v[70:71], v[70:71], v[88:89] op_sel_hi:[1,0]
	v_pk_mul_f32 v[72:73], v[72:73], v[88:89] op_sel_hi:[1,0]
	v_pk_mul_f32 v[92:93], v[94:95], v[92:93]
	v_pk_mul_f32 v[82:83], v[96:97], v[82:83]
	v_pk_mul_f32 v[66:67], v[66:67], v[88:89] op_sel_hi:[1,0]
	v_pk_mul_f32 v[68:69], v[68:69], v[88:89] op_sel_hi:[1,0]
	s_waitcnt vmcnt(1)
	v_pk_fma_f32 v[70:71], v[70:71], v[74:75], v[78:79]
	v_pk_fma_f32 v[72:73], v[72:73], v[76:77], v[80:81]
	v_pk_mul_f32 v[70:71], v[92:93], v[70:71]
	v_pk_mul_f32 v[72:73], v[82:83], v[72:73]
	v_cvt_pk_bf16_f32 v70, v70, v71
	v_cvt_pk_bf16_f32 v71, v72, v73
	global_store_dwordx2 v[86:87], v[70:71], off offset:192
	global_load_dwordx4 v[70:73], v[116:117], off offset:448
	s_nop 0
	global_load_dwordx4 v[74:77], v[118:119], off offset:448
	s_waitcnt vmcnt(3)
	v_lshlrev_b32_e32 v78, 16, v84
	v_and_b32_e32 v79, 0xffff0000, v84
	v_lshlrev_b32_e32 v80, 16, v85
	v_and_b32_e32 v81, 0xffff0000, v85
	v_mul_f32_e32 v82, 0xbfb8aa3b, v78
	v_mul_f32_e32 v83, 0xbfb8aa3b, v79
	v_mul_f32_e32 v84, 0xbfb8aa3b, v80
	v_mul_f32_e32 v85, 0xbfb8aa3b, v81
	v_exp_f32_e32 v82, v82
	v_exp_f32_e32 v83, v83
	v_exp_f32_e32 v84, v84
	v_exp_f32_e32 v85, v85
	v_add_f32_e32 v82, 1.0, v82
	v_add_f32_e32 v83, 1.0, v83
	v_add_f32_e32 v84, 1.0, v84
	v_add_f32_e32 v85, 1.0, v85
	v_rcp_f32_e32 v82, v82
	v_rcp_f32_e32 v83, v83
	v_rcp_f32_e32 v84, v84
	v_rcp_f32_e32 v85, v85
	v_pk_mul_f32 v[78:79], v[82:83], v[78:79]
	v_pk_mul_f32 v[80:81], v[84:85], v[80:81]
	s_waitcnt vmcnt(0)
	v_pk_fma_f32 v[66:67], v[66:67], v[70:71], v[74:75]
	v_pk_fma_f32 v[68:69], v[68:69], v[72:73], v[76:77]
	v_pk_mul_f32 v[66:67], v[78:79], v[66:67]
	v_pk_mul_f32 v[68:69], v[80:81], v[68:69]
	v_cvt_pk_bf16_f32 v66, v66, v67
	v_cvt_pk_bf16_f32 v67, v68, v69
	global_store_dwordx2 v[86:87], v[66:67], off offset:224
	s_cbranch_vccz .LBB0_1084
	s_add_i32 s6, s6, s82
	s_cmpk_gt_i32 s6, 0x1ff
	s_barrier
	s_cbranch_scc0 .LBB0_1083
